# MLA unit start: first QK MFMAs wait only for the Q fragment loads; second-stage K/V loads waited for at K/V loop entry
# baseline (speedup 1.0000x reference)
.LBB0_524:
	v_readlane_b32 s30, v251, 2
	v_readlane_b32 s31, v251, 3
	s_and_b64 s[38:39], s[30:31], exec
	v_readlane_b32 s0, v251, 25
	s_cselect_b32 s0, s0, s74
	s_and_b32 s36, s36, 15
	s_mul_i32 s30, s6, 0x600000
	s_mul_hi_i32 s13, s6, 0x600000
	s_add_u32 s30, s42, s30
	s_addc_u32 s13, s43, s13
	s_mul_i32 s31, s36, 0xc0
	s_add_u32 s38, s30, s31
	s_addc_u32 s39, s13, 0
	s_lshl_b32 s0, s0, 8
	s_and_b32 s0, s0, 0x700
	v_and_b32_e32 v10, 31, v4
	v_or_b32_e32 v5, s0, v10
	v_lshrrev_b32_e32 v104, 5, v0
	v_lshl_add_u32 v188, s16, 5, v5
	v_mov_b64_e32 v[6:7], s[38:39]
	v_mad_i64_i32 v[6:7], s[38:39], v188, s47, v[6:7]
	v_lshlrev_b32_e32 v8, 4, v104
	v_mov_b32_e32 v9, v1
	s_lshl_b64 s[16:17], s[16:17], 11
	v_lshl_add_u64 v[6:7], v[6:7], 0, v[8:9]
	v_lshlrev_b32_e32 v5, 4, v4
	v_or_b32_e32 v191, s17, v1
	v_or_b32_e32 v190, s16, v0
	s_cmp_gt_i32 s75, 0x9fff
	flat_load_dwordx4 v[106:109], v[6:7]
	flat_load_dwordx4 v[110:113], v[6:7] offset:32
	flat_load_dwordx4 v[114:117], v[6:7] offset:64
	flat_load_dwordx4 v[118:121], v[6:7] offset:96
	flat_load_dwordx4 v[122:125], v[6:7] offset:128
	flat_load_dwordx4 v[126:129], v[6:7] offset:160
	v_and_b32_e32 v219, 0xc0, v5
	v_lshlrev_b32_e32 v5, 1, v4
	v_lshlrev_b32_e32 v4, 3, v4
	s_cselect_b32 s0, s68, 0x14000
	v_lshl_add_u64 v[6:7], v[190:191], 4, s[14:15]
	s_mov_b64 s[14:15], 0x1000
	v_lshl_add_u64 v[2:3], s[18:19], 0, v[2:3]
	s_ashr_i32 s13, s12, 31
	v_and_b32_e32 v227, 32, v5
	v_and_b32_e32 v228, 24, v4
	v_lshl_add_u64 v[4:5], v[102:103], 1, s[24:25]
	s_add_i32 s0, s0, s75
	v_lshl_add_u64 v[8:9], v[6:7], 0, s[14:15]
	v_lshl_add_u64 v[2:3], v[2:3], 0, s[14:15]
	s_lshl_b64 s[14:15], s[12:13], 6
	s_waitcnt vmcnt(5)
	v_lshl_add_u64 v[4:5], v[4:5], 0, s[14:15]
	s_mov_b64 s[14:15], 0x4000
	s_add_i32 s13, s28, s0
	v_lshlrev_b32_e32 v229, 4, v10
	s_waitcnt lgkmcnt(0)
	s_barrier
	v_lshl_add_u64 v[10:11], v[4:5], 0, s[14:15]
	s_mov_b32 m0, s13
	s_mov_b64 s[14:15], 0x1400
	global_load_lds_dwordx4 v[8:9], off
	v_lshl_add_u64 v[6:7], v[6:7], 0, s[14:15]
	s_add_i32 m0, s13, 0x400
	s_add_i32 s13, s29, s0
	global_load_lds_dwordx4 v[6:7], off
	s_add_i32 m0, s13, 0x4000
	s_add_i32 s0, s37, s0
	global_load_lds_dwordx4 v[2:3], off
	s_add_i32 m0, s0, 0x6000
	s_mov_b64 s[14:15], 0x24000
	global_load_lds_dwordx4 v[10:11], off
	v_lshl_add_u64 v[2:3], v[4:5], 0, s[14:15]
	s_add_i32 m0, s0, 0x8000
	v_lshlrev_b32_e32 v0, 11, v104
	global_load_lds_dwordx4 v[2:3], off
	s_add_i32 s0, s75, 0
	v_add3_u32 v82, s0, v0, v229
	ds_read_b128 v[50:53], v82
	ds_read_b128 v[18:21], v82 offset:512
	ds_read_b128 v[54:57], v82 offset:4096
	ds_read_b128 v[22:25], v82 offset:4608
	ds_read_b128 v[58:61], v82 offset:8192
	ds_read_b128 v[26:29], v82 offset:8704
	ds_read_b128 v[62:65], v82 offset:12288
	ds_read_b128 v[30:33], v82 offset:12800
	ds_read_b128 v[66:69], v82 offset:16384
	ds_read_b128 v[70:73], v82 offset:16896
	ds_read_b128 v[74:77], v82 offset:20480
	ds_read_b128 v[78:81], v82 offset:20992
	v_lshlrev_b32_e32 v218, 8, v104
	v_add_u32_e32 v2, s0, v218
	v_add3_u32 v83, v2, v219, v227
	v_readlane_b32 s76, v249, 60
	v_readlane_b32 s77, v249, 61
	v_readlane_b32 s78, v249, 62
	v_readlane_b32 s79, v249, 63
	v_readlane_b32 s80, v248, 0
	v_readlane_b32 s81, v248, 1
	v_readlane_b32 s82, v248, 2
	v_readlane_b32 s83, v248, 3
	v_readlane_b32 s84, v248, 4
	v_readlane_b32 s85, v248, 5
	v_readlane_b32 s86, v248, 6
	v_readlane_b32 s87, v248, 7
	v_readlane_b32 s88, v248, 8
	v_readlane_b32 s89, v248, 9
	v_readlane_b32 s90, v248, 10
	v_readlane_b32 s91, v248, 11
	v_mov_b64_e32 v[34:35], s[76:77]
	v_mov_b64_e32 v[36:37], s[78:79]
	v_mov_b64_e32 v[38:39], s[80:81]
	v_mov_b64_e32 v[40:41], s[82:83]
	v_mov_b64_e32 v[42:43], s[84:85]
	v_mov_b64_e32 v[44:45], s[86:87]
	v_mov_b64_e32 v[46:47], s[88:89]
	v_mov_b64_e32 v[48:49], s[90:91]
	s_waitcnt vmcnt(5) lgkmcnt(0)
	s_nop 0
	v_mfma_f32_32x32x16_bf16 v[2:17], v[18:21], v[106:109], v[34:49]
	v_mfma_f32_32x32x16_bf16 v[2:17], v[22:25], v[110:113], v[2:17]
	v_mfma_f32_32x32x16_bf16 v[2:17], v[26:29], v[114:117], v[2:17]
	v_mfma_f32_32x32x16_bf16 v[2:17], v[30:33], v[118:121], v[2:17]
	v_mfma_f32_32x32x16_bf16 v[2:17], v[70:73], v[122:125], v[2:17]
	v_mfma_f32_32x32x16_bf16 v[2:17], v[78:81], v[126:129], v[2:17]
	v_mfma_f32_32x32x16_bf16 v[18:33], v[50:53], v[106:109], v[34:49]
	v_add_u32_e32 v105, v83, v228
	ds_read_b128 v[70:73], v82 offset:1024
	ds_read_b128 v[130:133], v82 offset:1536
	ds_read_b128 v[78:81], v82 offset:5120
	ds_read_b128 v[134:137], v82 offset:5632
	ds_read_b128 v[138:141], v82 offset:9216
	ds_read_b128 v[142:145], v82 offset:9728
	v_mfma_f32_32x32x16_bf16 v[18:33], v[54:57], v[110:113], v[18:33]
	ds_read_b128 v[146:149], v82 offset:13312
	ds_read_b128 v[150:153], v82 offset:13824
	ds_read_b128 v[154:157], v82 offset:17408
	ds_read_b128 v[158:161], v82 offset:17920
	ds_read_b128 v[162:165], v82 offset:21504
	ds_read_b128 v[98:101], v82 offset:22016
	ds_read_b64_tr_b16 v[82:83], v105 offset:24576
	v_mfma_f32_32x32x16_bf16 v[18:33], v[58:61], v[114:117], v[18:33]
	ds_read_b64_tr_b16 v[84:85], v105 offset:25088
	ds_read_b64_tr_b16 v[86:87], v105 offset:25600
	ds_read_b64_tr_b16 v[88:89], v105 offset:26112
	ds_read_b64_tr_b16 v[90:91], v105 offset:26624
	ds_read_b64_tr_b16 v[92:93], v105 offset:27136
	ds_read_b64_tr_b16 v[94:95], v105 offset:27648
	ds_read_b64_tr_b16 v[96:97], v105 offset:28160
	v_mfma_f32_32x32x16_bf16 v[18:33], v[62:65], v[118:121], v[18:33]
	v_mfma_f32_32x32x16_bf16 v[18:33], v[66:69], v[122:125], v[18:33]
	v_mfma_f32_32x32x16_bf16 v[18:33], v[74:77], v[126:129], v[18:33]
	v_max_f32_e32 v34, v2, v2
	s_nop 10
	v_max_f32_e32 v35, v18, v18
	v_max_f32_e32 v34, v35, v34
	v_max3_f32 v34, v34, v19, v3
	v_max3_f32 v34, v34, v20, v4
	v_max3_f32 v34, v34, v21, v5
	v_max3_f32 v34, v34, v22, v6
	v_max3_f32 v34, v34, v23, v7
	v_max3_f32 v34, v34, v24, v8
	v_max3_f32 v34, v34, v25, v9
	v_max3_f32 v34, v34, v26, v10
	v_max3_f32 v34, v34, v27, v11
	v_max3_f32 v34, v34, v28, v12
	v_max3_f32 v34, v34, v29, v13
	v_max3_f32 v34, v34, v30, v14
	v_max3_f32 v34, v34, v31, v15
	v_max3_f32 v34, v34, v32, v16
	v_max3_f32 v34, v34, v33, v17
	v_mov_b32_e32 v35, v34
	s_nop 1
	v_permlane32_swap_b32_e32 v34, v35
	v_max_f32_e32 v35, v35, v35
	v_max_f32_e32 v34, v34, v34
	v_max_f32_e32 v40, v34, v35
	v_sub_f32_e32 v34, v2, v40
	v_sub_f32_e32 v2, v18, v40
	v_sub_f32_e32 v35, v3, v40
	v_sub_f32_e32 v36, v4, v40
	v_sub_f32_e32 v4, v19, v40
	v_exp_f32_e32 v2, v2
	v_exp_f32_e32 v3, v34
	v_sub_f32_e32 v37, v5, v40
	v_sub_f32_e32 v38, v6, v40
	v_sub_f32_e32 v6, v20, v40
	v_exp_f32_e32 v4, v4
	v_exp_f32_e32 v5, v35
	v_sub_f32_e32 v39, v7, v40
	v_sub_f32_e32 v41, v8, v40
	v_sub_f32_e32 v8, v21, v40
	v_exp_f32_e32 v6, v6
	v_exp_f32_e32 v7, v36
	v_sub_f32_e32 v42, v9, v40
	v_sub_f32_e32 v45, v12, v40
	v_sub_f32_e32 v12, v22, v40
	v_exp_f32_e32 v8, v8
	v_exp_f32_e32 v9, v37
	v_sub_f32_e32 v43, v10, v40
	v_sub_f32_e32 v44, v11, v40
	v_sub_f32_e32 v46, v13, v40
	v_sub_f32_e32 v47, v14, v40
	v_sub_f32_e32 v14, v23, v40
	v_pk_add_f32 v[10:11], v[2:3], 0 op_sel_hi:[1,0]
	v_exp_f32_e32 v12, v12
	v_exp_f32_e32 v13, v38
	v_sub_f32_e32 v48, v15, v40
	v_sub_f32_e32 v49, v16, v40
	v_sub_f32_e32 v16, v24, v40
	v_pk_add_f32 v[10:11], v[4:5], v[10:11]
	v_exp_f32_e32 v14, v14
	v_exp_f32_e32 v15, v39
	v_sub_f32_e32 v50, v17, v40
	v_sub_f32_e32 v18, v25, v40
	v_pk_add_f32 v[10:11], v[6:7], v[10:11]
	v_exp_f32_e32 v16, v16
	v_exp_f32_e32 v17, v41
	v_sub_f32_e32 v19, v26, v40
	v_pk_add_f32 v[10:11], v[8:9], v[10:11]
	v_exp_f32_e32 v22, v18
	v_exp_f32_e32 v23, v42
	v_sub_f32_e32 v20, v27, v40
	v_exp_f32_e32 v24, v19
	v_exp_f32_e32 v25, v43
	v_pk_add_f32 v[10:11], v[12:13], v[10:11]
	v_sub_f32_e32 v21, v28, v40
	v_exp_f32_e32 v26, v20
	v_exp_f32_e32 v27, v44
	v_pk_add_f32 v[10:11], v[14:15], v[10:11]
	v_sub_f32_e32 v51, v29, v40
	v_exp_f32_e32 v28, v21
	v_exp_f32_e32 v29, v45
	v_pk_add_f32 v[10:11], v[16:17], v[10:11]
	v_sub_f32_e32 v52, v30, v40
	v_sub_f32_e32 v53, v31, v40
	v_exp_f32_e32 v30, v51
	v_exp_f32_e32 v31, v46
	v_pk_add_f32 v[10:11], v[22:23], v[10:11]
	v_sub_f32_e32 v54, v32, v40
	v_sub_f32_e32 v55, v33, v40
	v_exp_f32_e32 v32, v52
	v_exp_f32_e32 v33, v47
	v_pk_add_f32 v[10:11], v[24:25], v[10:11]
	v_exp_f32_e32 v34, v53
	v_exp_f32_e32 v35, v48
	v_pk_add_f32 v[10:11], v[26:27], v[10:11]
	v_exp_f32_e32 v36, v54
	v_exp_f32_e32 v37, v49
	v_pk_add_f32 v[10:11], v[28:29], v[10:11]
	v_exp_f32_e32 v38, v55
	v_exp_f32_e32 v39, v50
	v_pk_add_f32 v[10:11], v[30:31], v[10:11]
	v_cvt_pk_bf16_f32 v18, v2, v4
	v_pk_add_f32 v[10:11], v[32:33], v[10:11]
	v_cvt_pk_bf16_f32 v170, v3, v5
	v_pk_add_f32 v[10:11], v[34:35], v[10:11]
	v_cvt_pk_bf16_f32 v168, v32, v34
	v_pk_add_f32 v[10:11], v[36:37], v[10:11]
	v_cvt_pk_bf16_f32 v19, v6, v8
	v_pk_add_f32 v[10:11], v[38:39], v[10:11]
	v_cvt_pk_bf16_f32 v20, v12, v14
	v_pk_add_f32 v[2:3], v[10:11], v[10:11] op_sel:[0,1] op_sel_hi:[1,0]
	v_cvt_pk_bf16_f32 v21, v16, v22
	v_mov_b32_e32 v3, v40
	v_pk_add_f32 v[214:215], v[2:3], 0 op_sel_hi:[1,0]
	v_cvt_pk_bf16_f32 v169, v36, v38
	v_xor_b32_e32 v34, 0x80000000, v215
	v_cvt_pk_bf16_f32 v176, v33, v35
	v_cvt_pk_bf16_f32 v177, v37, v39
	v_mov_b32_e32 v35, v34
	v_mov_b32_e32 v36, v34
	v_mov_b32_e32 v37, v34
	v_mov_b32_e32 v38, v34
	v_mov_b32_e32 v39, v34
	v_mov_b32_e32 v40, v34
	v_mov_b32_e32 v41, v34
	v_mov_b32_e32 v42, v34
	v_mov_b32_e32 v43, v34
	v_mov_b32_e32 v44, v34
	v_mov_b32_e32 v45, v34
	v_mov_b32_e32 v46, v34
	v_mov_b32_e32 v47, v34
	v_mov_b32_e32 v48, v34
	v_mov_b32_e32 v49, v34
	v_cvt_pk_bf16_f32 v166, v24, v26
	v_cvt_pk_bf16_f32 v167, v28, v30
	v_cvt_pk_bf16_f32 v171, v7, v9
	v_cvt_pk_bf16_f32 v172, v13, v15
	v_cvt_pk_bf16_f32 v173, v17, v23
	v_cvt_pk_bf16_f32 v174, v25, v27
	v_cvt_pk_bf16_f32 v175, v29, v31
	s_waitcnt lgkmcnt(14)
	v_mfma_f32_32x32x16_bf16 v[50:65], v[70:73], v[106:109], v[34:49]
	v_mfma_f32_32x32x16_bf16 v[50:65], v[78:81], v[110:113], v[50:65]
	v_mfma_f32_32x32x16_bf16 v[50:65], v[138:141], v[114:117], v[50:65]
	s_waitcnt lgkmcnt(13)
	v_mfma_f32_32x32x16_bf16 v[50:65], v[146:149], v[118:121], v[50:65]
	s_waitcnt lgkmcnt(11)
	v_mfma_f32_32x32x16_bf16 v[50:65], v[154:157], v[122:125], v[50:65]
	s_waitcnt lgkmcnt(9)
	v_mfma_f32_32x32x16_bf16 v[50:65], v[162:165], v[126:129], v[50:65]
	v_mfma_f32_32x32x16_bf16 v[66:81], v[130:133], v[106:109], v[34:49]
	v_mfma_f32_32x32x16_bf16 v[66:81], v[134:137], v[110:113], v[66:81]
	v_mfma_f32_32x32x16_bf16 v[66:81], v[142:145], v[114:117], v[66:81]
	v_mfma_f32_32x32x16_bf16 v[66:81], v[150:153], v[118:121], v[66:81]
	v_mfma_f32_32x32x16_bf16 v[66:81], v[158:161], v[122:125], v[66:81]
	s_waitcnt lgkmcnt(8)
	v_mfma_f32_32x32x16_bf16 v[66:81], v[98:101], v[126:129], v[66:81]
	s_barrier
	ds_read_b64_tr_b16 v[22:23], v105 offset:32768
	ds_read_b64_tr_b16 v[24:25], v105 offset:33280
	ds_read_b64_tr_b16 v[98:99], v105 offset:33792
	ds_read_b64_tr_b16 v[100:101], v105 offset:34304
	ds_read_b64_tr_b16 v[130:131], v105 offset:34816
	ds_read_b64_tr_b16 v[132:133], v105 offset:35328
	ds_read_b64_tr_b16 v[134:135], v105 offset:35840
	ds_read_b64_tr_b16 v[136:137], v105 offset:36352
	s_waitcnt lgkmcnt(14)
	v_mfma_f32_32x32x16_bf16 v[2:17], v[82:85], v[18:21], 0
	s_nop 1
	v_max_f32_e32 v82, v66, v66
	v_max_f32_e32 v83, v50, v50
	v_max_f32_e32 v82, v83, v82
	s_waitcnt lgkmcnt(12)
	v_mfma_f32_32x32x16_bf16 v[2:17], v[86:89], v[166:169], v[2:17]
	v_max3_f32 v82, v82, v51, v67
	v_max3_f32 v82, v82, v52, v68
	v_max3_f32 v82, v82, v53, v69
	s_waitcnt lgkmcnt(10)
	v_mfma_f32_32x32x16_bf16 v[2:17], v[90:93], v[170:173], v[2:17]
	v_max3_f32 v82, v82, v54, v70
	v_max3_f32 v82, v82, v55, v71
	v_max3_f32 v82, v82, v56, v72
	s_waitcnt lgkmcnt(8)
	v_mfma_f32_32x32x16_bf16 v[2:17], v[94:97], v[174:177], v[2:17]
	v_max3_f32 v82, v82, v57, v73
	v_max3_f32 v82, v82, v58, v74
	v_max3_f32 v82, v82, v59, v75
	s_waitcnt lgkmcnt(6)
	v_mfma_f32_32x32x16_bf16 v[18:33], v[22:25], v[18:21], 0
	v_max3_f32 v82, v82, v60, v76
	v_max3_f32 v82, v82, v61, v77
	v_max3_f32 v82, v82, v62, v78
	s_waitcnt lgkmcnt(4)
	v_mfma_f32_32x32x16_bf16 v[18:33], v[98:101], v[166:169], v[18:33]
	v_max3_f32 v82, v82, v63, v79
	v_max3_f32 v82, v82, v64, v80
	v_max3_f32 v82, v82, v65, v81
	s_waitcnt lgkmcnt(2)
	v_mfma_f32_32x32x16_bf16 v[18:33], v[130:133], v[170:173], v[18:33]
	v_mov_b32_e32 v83, v82
	s_nop 1
	v_permlane32_swap_b32_e32 v82, v83
	v_max_f32_e32 v83, v83, v83
	v_max_f32_e32 v82, v82, v82
	v_max_f32_e32 v82, v82, v83
	s_waitcnt lgkmcnt(0)
	v_mfma_f32_32x32x16_bf16 v[18:33], v[134:137], v[174:177], v[18:33]
	v_cmp_lt_f32_e32 vcc, s69, v82
	s_cbranch_vccz .LBB0_526
	v_max_f32_e32 v34, v82, v82
	v_max_f32_e32 v34, 0, v34
	v_exp_f32_e64 v36, -v34
	v_pk_add_f32 v[50:51], v[50:51], v[34:35] op_sel_hi:[1,0] neg_lo:[0,1] neg_hi:[0,1]
	v_pk_add_f32 v[66:67], v[66:67], v[34:35] op_sel_hi:[1,0] neg_lo:[0,1] neg_hi:[0,1]
	v_pk_add_f32 v[52:53], v[52:53], v[34:35] op_sel_hi:[1,0] neg_lo:[0,1] neg_hi:[0,1]
	v_pk_mul_f32 v[82:83], v[214:215], v[36:37]
	v_add_f32_e32 v215, v215, v34
	v_pk_add_f32 v[68:69], v[68:69], v[34:35] op_sel_hi:[1,0] neg_lo:[0,1] neg_hi:[0,1]
	v_pk_add_f32 v[54:55], v[54:55], v[34:35] op_sel_hi:[1,0] neg_lo:[0,1] neg_hi:[0,1]
	v_pk_add_f32 v[70:71], v[70:71], v[34:35] op_sel_hi:[1,0] neg_lo:[0,1] neg_hi:[0,1]
	v_pk_add_f32 v[56:57], v[56:57], v[34:35] op_sel_hi:[1,0] neg_lo:[0,1] neg_hi:[0,1]
	v_pk_add_f32 v[72:73], v[72:73], v[34:35] op_sel_hi:[1,0] neg_lo:[0,1] neg_hi:[0,1]
	v_pk_add_f32 v[58:59], v[58:59], v[34:35] op_sel_hi:[1,0] neg_lo:[0,1] neg_hi:[0,1]
	v_pk_add_f32 v[74:75], v[74:75], v[34:35] op_sel_hi:[1,0] neg_lo:[0,1] neg_hi:[0,1]
	v_pk_add_f32 v[60:61], v[60:61], v[34:35] op_sel_hi:[1,0] neg_lo:[0,1] neg_hi:[0,1]
	v_pk_add_f32 v[76:77], v[76:77], v[34:35] op_sel_hi:[1,0] neg_lo:[0,1] neg_hi:[0,1]
	v_pk_add_f32 v[62:63], v[62:63], v[34:35] op_sel_hi:[1,0] neg_lo:[0,1] neg_hi:[0,1]
	v_pk_add_f32 v[78:79], v[78:79], v[34:35] op_sel_hi:[1,0] neg_lo:[0,1] neg_hi:[0,1]
	v_pk_add_f32 v[64:65], v[64:65], v[34:35] op_sel_hi:[1,0] neg_lo:[0,1] neg_hi:[0,1]
	v_pk_add_f32 v[80:81], v[80:81], v[34:35] op_sel_hi:[1,0] neg_lo:[0,1] neg_hi:[0,1]
	v_xor_b32_e32 v34, 0x80000000, v215
	v_pk_mul_f32 v[16:17], v[16:17], v[36:37] op_sel_hi:[1,0]
	v_pk_mul_f32 v[14:15], v[14:15], v[36:37] op_sel_hi:[1,0]
	v_pk_mul_f32 v[12:13], v[12:13], v[36:37] op_sel_hi:[1,0]
	v_pk_mul_f32 v[10:11], v[10:11], v[36:37] op_sel_hi:[1,0]
	v_pk_mul_f32 v[8:9], v[8:9], v[36:37] op_sel_hi:[1,0]
	v_pk_mul_f32 v[6:7], v[6:7], v[36:37] op_sel_hi:[1,0]
	v_pk_mul_f32 v[4:5], v[4:5], v[36:37] op_sel_hi:[1,0]
	v_pk_mul_f32 v[2:3], v[2:3], v[36:37] op_sel_hi:[1,0]
	v_pk_mul_f32 v[32:33], v[32:33], v[36:37] op_sel_hi:[1,0]
	v_pk_mul_f32 v[30:31], v[30:31], v[36:37] op_sel_hi:[1,0]
	v_pk_mul_f32 v[28:29], v[28:29], v[36:37] op_sel_hi:[1,0]
	v_pk_mul_f32 v[26:27], v[26:27], v[36:37] op_sel_hi:[1,0]
	v_pk_mul_f32 v[24:25], v[24:25], v[36:37] op_sel_hi:[1,0]
	v_pk_mul_f32 v[22:23], v[22:23], v[36:37] op_sel_hi:[1,0]
	v_pk_mul_f32 v[20:21], v[20:21], v[36:37] op_sel_hi:[1,0]
	v_pk_mul_f32 v[18:19], v[18:19], v[36:37] op_sel_hi:[1,0]
	v_mov_b32_e32 v35, v34
	v_mov_b32_e32 v36, v34
	v_mov_b32_e32 v37, v34
	v_mov_b32_e32 v38, v34
	v_mov_b32_e32 v39, v34
	v_mov_b32_e32 v40, v34
	v_mov_b32_e32 v41, v34
	v_mov_b32_e32 v42, v34
	v_mov_b32_e32 v43, v34
	v_mov_b32_e32 v44, v34
	v_mov_b32_e32 v45, v34
	v_mov_b32_e32 v46, v34
	v_mov_b32_e32 v47, v34
	v_mov_b32_e32 v48, v34
	v_mov_b32_e32 v49, v34
	v_mov_b32_e32 v214, v82
.LBB0_526:
	ds_read_b64_tr_b16 v[82:83], v105 offset:28672
	ds_read_b64_tr_b16 v[84:85], v105 offset:29184
	ds_read_b64_tr_b16 v[86:87], v105 offset:29696
	ds_read_b64_tr_b16 v[88:89], v105 offset:30208
	ds_read_b64_tr_b16 v[90:91], v105 offset:30720
	ds_read_b64_tr_b16 v[92:93], v105 offset:31232
	ds_read_b64_tr_b16 v[94:95], v105 offset:31744
	ds_read_b64_tr_b16 v[96:97], v105 offset:32256
	s_add_i32 s74, s74, 1
	v_readlane_b32 s14, v251, 2
	s_ashr_i32 s0, s74, 3
	s_add_i32 s4, s4, 4
	v_readlane_b32 s15, v251, 3
	s_and_b64 s[14:15], s[14:15], exec
	s_cselect_b32 s14, s4, s0
	s_ashr_i32 s16, s14, 4
	s_ashr_i32 s15, s14, 31
	s_ashr_i32 s17, s16, 31
	s_lshl_b64 s[14:15], s[14:15], 18
	s_lshl_b64 s[16:17], s[16:17], 17
	s_cmp_ge_i32 s74, s1
	v_ashrrev_i32_e32 v189, 31, v188
	v_lshlrev_b32_e32 v230, 3, v104
	s_mov_b32 s13, 1
	s_cselect_b64 s[18:19], -1, 0
	v_exp_f32_e32 v99, v50
	v_exp_f32_e32 v98, v66
	v_exp_f32_e32 v101, v51
	v_exp_f32_e32 v100, v67
	v_exp_f32_e32 v67, v52
	v_exp_f32_e32 v66, v68
	v_exp_f32_e32 v131, v53
	v_exp_f32_e32 v130, v69
	v_pk_add_f32 v[50:51], v[98:99], 0 op_sel_hi:[1,0]
	v_exp_f32_e32 v69, v54
	v_exp_f32_e32 v68, v70
	v_pk_add_f32 v[50:51], v[100:101], v[50:51]
	v_exp_f32_e32 v133, v55
	v_exp_f32_e32 v132, v71
	v_pk_add_f32 v[50:51], v[66:67], v[50:51]
	v_exp_f32_e32 v71, v56
	v_exp_f32_e32 v70, v72
	v_pk_add_f32 v[50:51], v[130:131], v[50:51]
	v_exp_f32_e32 v135, v57
	v_exp_f32_e32 v134, v73
	v_exp_f32_e32 v73, v58
	v_exp_f32_e32 v72, v74
	v_pk_add_f32 v[50:51], v[68:69], v[50:51]
	v_exp_f32_e32 v137, v59
	v_exp_f32_e32 v136, v75
	v_pk_add_f32 v[50:51], v[132:133], v[50:51]
	v_exp_f32_e32 v75, v60
	v_exp_f32_e32 v74, v76
	v_pk_add_f32 v[50:51], v[70:71], v[50:51]
	v_exp_f32_e32 v139, v61
	v_exp_f32_e32 v138, v77
	v_pk_add_f32 v[50:51], v[134:135], v[50:51]
	v_exp_f32_e32 v77, v62
	v_exp_f32_e32 v76, v78
	v_pk_add_f32 v[50:51], v[72:73], v[50:51]
	v_exp_f32_e32 v141, v63
	v_exp_f32_e32 v140, v79
	v_pk_add_f32 v[50:51], v[136:137], v[50:51]
	v_exp_f32_e32 v79, v64
	v_exp_f32_e32 v78, v80
	v_pk_add_f32 v[50:51], v[74:75], v[50:51]
	v_exp_f32_e32 v143, v65
	v_exp_f32_e32 v142, v81
	v_pk_add_f32 v[50:51], v[138:139], v[50:51]
	v_cvt_pk_bf16_f32 v52, v69, v133
	v_pk_add_f32 v[50:51], v[76:77], v[50:51]
	v_cvt_pk_bf16_f32 v53, v71, v135
	v_pk_add_f32 v[50:51], v[140:141], v[50:51]
	v_cvt_pk_bf16_f32 v54, v73, v137
	v_pk_add_f32 v[50:51], v[78:79], v[50:51]
	v_cvt_pk_bf16_f32 v55, v75, v139
	v_pk_add_f32 v[144:145], v[142:143], v[50:51]
	v_cvt_pk_bf16_f32 v51, v67, v131
	v_cvt_pk_bf16_f32 v56, v77, v141
	v_cvt_pk_bf16_f32 v57, v79, v143
	v_cvt_pk_bf16_f32 v59, v66, v130
	v_cvt_pk_bf16_f32 v60, v68, v132
	v_cvt_pk_bf16_f32 v61, v70, v134
	v_cvt_pk_bf16_f32 v62, v72, v136
	v_cvt_pk_bf16_f32 v63, v74, v138
	v_cvt_pk_bf16_f32 v64, v76, v140
	v_cvt_pk_bf16_f32 v65, v78, v142
	ds_read_b64_tr_b16 v[66:67], v105 offset:36864
	ds_read_b64_tr_b16 v[68:69], v105 offset:37376
	ds_read_b64_tr_b16 v[70:71], v105 offset:37888
	ds_read_b64_tr_b16 v[72:73], v105 offset:38400
	ds_read_b64_tr_b16 v[74:75], v105 offset:38912
	ds_read_b64_tr_b16 v[76:77], v105 offset:39424
	ds_read_b64_tr_b16 v[78:79], v105 offset:39936
	ds_read_b64_tr_b16 v[80:81], v105 offset:40448
	v_cvt_pk_bf16_f32 v50, v99, v101
	v_cvt_pk_bf16_f32 v58, v98, v100
	s_waitcnt lgkmcnt(14)
	v_mfma_f32_32x32x16_bf16 v[2:17], v[82:85], v[50:53], v[2:17]
	s_add_i32 s0, s75, 0xa000
	s_cmp_lt_i32 s75, 0x14000
	s_cselect_b32 s75, s0, 0
	v_lshl_add_u64 v[216:217], v[102:103], 1, s[2:3]
	s_movk_i32 s38, 0x80
	s_waitcnt lgkmcnt(6)
	v_mfma_f32_32x32x16_bf16 v[18:33], v[66:69], v[50:53], v[18:33]
	v_add_f32_e32 v50, v144, v145
	v_add_f32_e32 v231, v214, v50
	v_mfma_f32_32x32x16_bf16 v[2:17], v[86:89], v[54:57], v[2:17]
	s_waitcnt lgkmcnt(4)
	v_mfma_f32_32x32x16_bf16 v[18:33], v[70:73], v[54:57], v[18:33]
	v_mfma_f32_32x32x16_bf16 v[2:17], v[90:93], v[58:61], v[2:17]
	s_waitcnt lgkmcnt(2)
	v_mfma_f32_32x32x16_bf16 v[18:33], v[74:77], v[58:61], v[18:33]
	v_mfma_f32_32x32x16_bf16 v[2:17], v[94:97], v[62:65], v[2:17]
	s_waitcnt lgkmcnt(0)
	v_mfma_f32_32x32x16_bf16 v[18:33], v[78:81], v[62:65], v[18:33]
	s_waitcnt vmcnt(0)
	s_branch .LBB0_528
